# GEMM K-loops: s_setprio 1 issued before the segment barrier and redundant counted lgkmcnt waits dropped so the first MFMA issues right after barrier release; plus down-proj full-line stores and 64B-al
# speedup vs baseline: 1.0106x; 1.0106x over previous
.LBB0_129:
	ds_read_b128 v[132:135], v155
	ds_read_b128 v[136:139], v155 offset:1024
	ds_read_b128 v[140:143], v155 offset:2048
	ds_read_b128 v[160:163], v155 offset:3072
	ds_read_b128 v[164:167], v156
	ds_read_b128 v[168:171], v156 offset:1024
	ds_read_b128 v[172:175], v156 offset:2048
	ds_read_b128 v[176:179], v156 offset:3072
	s_cmp_eq_u32 s82, 28
	s_cselect_b32 s36, s27, s78
	s_cselect_b32 s37, s21, s79
	s_cselect_b32 s34, s77, s80
	s_cselect_b32 s35, s19, s81
	s_add_u32 s30, s36, 0x8000
	s_addc_u32 s31, s37, 0
	ds_read_b128 v[180:183], v157
	ds_read_b128 v[184:187], v157 offset:1024
	ds_read_b128 v[188:191], v157 offset:2048
	ds_read_b128 v[192:195], v157 offset:3072
	ds_read_b128 v[196:199], v157 offset:4096
	ds_read_b128 v[200:203], v157 offset:5120
	ds_read_b128 v[204:207], v157 offset:6144
	ds_read_b128 v[208:211], v157 offset:7168
	s_add_u32 s84, s78, 0xffffc000
	s_addc_u32 s85, s79, -1
	s_mov_b32 m0, s74
	s_nop 0
	global_load_lds_dwordx4 v151, s[84:85]
	s_nop 0
	s_mov_b32 m0, s75
	s_nop 0
	global_load_lds_dwordx4 v153, s[84:85]
	s_waitcnt vmcnt(8)
	s_waitcnt lgkmcnt(0)
	s_setprio 1
	s_barrier
	v_mfma_i32_16x16x64_i8 v[124:127], v[132:135], v[180:183], v[124:127]
	v_mfma_i32_16x16x64_i8 v[120:123], v[140:143], v[180:183], v[120:123]
	v_mfma_i32_16x16x64_i8 v[116:119], v[132:135], v[188:191], v[116:119]
	v_mfma_i32_16x16x64_i8 v[112:115], v[140:143], v[188:191], v[112:115]
	v_mfma_i32_16x16x64_i8 v[108:111], v[132:135], v[196:199], v[108:111]
	v_mfma_i32_16x16x64_i8 v[104:107], v[140:143], v[196:199], v[104:107]
	v_mfma_i32_16x16x64_i8 v[100:103], v[132:135], v[204:207], v[100:103]
	v_mfma_i32_16x16x64_i8 v[96:99], v[140:143], v[204:207], v[96:99]
	v_mfma_i32_16x16x64_i8 v[124:127], v[136:139], v[184:187], v[124:127]
	v_mfma_i32_16x16x64_i8 v[120:123], v[160:163], v[184:187], v[120:123]
	v_mfma_i32_16x16x64_i8 v[116:119], v[136:139], v[192:195], v[116:119]
	v_mfma_i32_16x16x64_i8 v[112:115], v[160:163], v[192:195], v[112:115]
	v_mfma_i32_16x16x64_i8 v[108:111], v[136:139], v[200:203], v[108:111]
	v_mfma_i32_16x16x64_i8 v[104:107], v[160:163], v[200:203], v[104:107]
	v_mfma_i32_16x16x64_i8 v[100:103], v[136:139], v[208:211], v[100:103]
	v_mfma_i32_16x16x64_i8 v[96:99], v[160:163], v[208:211], v[96:99]
	s_setprio 0
	s_setprio 1
	v_mfma_i32_16x16x64_i8 v[92:95], v[164:167], v[180:183], v[92:95]
	v_mfma_i32_16x16x64_i8 v[88:91], v[172:175], v[180:183], v[88:91]
	v_mfma_i32_16x16x64_i8 v[84:87], v[164:167], v[188:191], v[84:87]
	v_mfma_i32_16x16x64_i8 v[80:83], v[172:175], v[188:191], v[80:83]
	v_mfma_i32_16x16x64_i8 v[76:79], v[164:167], v[196:199], v[76:79]
	v_mfma_i32_16x16x64_i8 v[72:75], v[172:175], v[196:199], v[72:75]
	v_mfma_i32_16x16x64_i8 v[68:71], v[164:167], v[204:207], v[68:71]
	v_mfma_i32_16x16x64_i8 v[64:67], v[172:175], v[204:207], v[64:67]
	v_mfma_i32_16x16x64_i8 v[92:95], v[168:171], v[184:187], v[92:95]
	v_mfma_i32_16x16x64_i8 v[88:91], v[176:179], v[184:187], v[88:91]
	v_mfma_i32_16x16x64_i8 v[84:87], v[168:171], v[192:195], v[84:87]
	v_mfma_i32_16x16x64_i8 v[80:83], v[176:179], v[192:195], v[80:83]
	v_mfma_i32_16x16x64_i8 v[76:79], v[168:171], v[200:203], v[76:79]
	v_mfma_i32_16x16x64_i8 v[72:75], v[176:179], v[200:203], v[72:75]
	v_mfma_i32_16x16x64_i8 v[68:71], v[168:171], v[208:211], v[68:71]
	v_mfma_i32_16x16x64_i8 v[64:67], v[176:179], v[208:211], v[64:67]
	s_setprio 0
	s_barrier
	ds_read_b128 v[180:183], v157 offset:16384
	ds_read_b128 v[184:187], v157 offset:17408
	ds_read_b128 v[188:191], v157 offset:18432
	ds_read_b128 v[192:195], v157 offset:19456
	ds_read_b128 v[196:199], v157 offset:20480
	ds_read_b128 v[200:203], v157 offset:21504
	ds_read_b128 v[204:207], v157 offset:22528
	ds_read_b128 v[208:211], v157 offset:23552
	s_mov_b32 m0, s29
	s_nop 0
	global_load_lds_dwordx4 v152, s[34:35]
	s_add_u32 s84, s34, 0x4000
	s_mov_b32 m0, s62
	s_nop 0
	global_load_lds_dwordx4 v154, s[34:35]
	s_addc_u32 s85, s35, 0
	s_mov_b32 m0, s63
	s_nop 0
	global_load_lds_dwordx4 v152, s[84:85]
	s_nop 0
	s_mov_b32 m0, s64
	s_nop 0
	global_load_lds_dwordx4 v154, s[84:85]
	s_nop 0
	s_mov_b32 m0, s61
	s_nop 0
	global_load_lds_dwordx4 v151, s[36:37]
	s_nop 0
	s_mov_b32 m0, s65
	s_nop 0
	global_load_lds_dwordx4 v153, s[36:37]
	s_waitcnt vmcnt(8)
	s_waitcnt lgkmcnt(0)
	s_setprio 1
	s_barrier
	v_mfma_i32_16x16x64_i8 v[60:63], v[132:135], v[180:183], v[60:63]
	v_mfma_i32_16x16x64_i8 v[56:59], v[140:143], v[180:183], v[56:59]
	v_mfma_i32_16x16x64_i8 v[52:55], v[132:135], v[188:191], v[52:55]
	v_mfma_i32_16x16x64_i8 v[48:51], v[140:143], v[188:191], v[48:51]
	v_mfma_i32_16x16x64_i8 v[44:47], v[132:135], v[196:199], v[44:47]
	v_mfma_i32_16x16x64_i8 v[40:43], v[140:143], v[196:199], v[40:43]
	v_mfma_i32_16x16x64_i8 v[36:39], v[132:135], v[204:207], v[36:39]
	v_mfma_i32_16x16x64_i8 v[32:35], v[140:143], v[204:207], v[32:35]
	v_mfma_i32_16x16x64_i8 v[60:63], v[136:139], v[184:187], v[60:63]
	v_mfma_i32_16x16x64_i8 v[56:59], v[160:163], v[184:187], v[56:59]
	v_mfma_i32_16x16x64_i8 v[52:55], v[136:139], v[192:195], v[52:55]
	v_mfma_i32_16x16x64_i8 v[48:51], v[160:163], v[192:195], v[48:51]
	v_mfma_i32_16x16x64_i8 v[44:47], v[136:139], v[200:203], v[44:47]
	v_mfma_i32_16x16x64_i8 v[40:43], v[160:163], v[200:203], v[40:43]
	v_mfma_i32_16x16x64_i8 v[36:39], v[136:139], v[208:211], v[36:39]
	v_mfma_i32_16x16x64_i8 v[32:35], v[160:163], v[208:211], v[32:35]
	s_setprio 0
	s_setprio 1
	v_mfma_i32_16x16x64_i8 v[28:31], v[164:167], v[180:183], v[28:31]
	v_mfma_i32_16x16x64_i8 v[24:27], v[172:175], v[180:183], v[24:27]
	v_mfma_i32_16x16x64_i8 v[20:23], v[164:167], v[188:191], v[20:23]
	v_mfma_i32_16x16x64_i8 v[16:19], v[172:175], v[188:191], v[16:19]
	v_mfma_i32_16x16x64_i8 v[12:15], v[164:167], v[196:199], v[12:15]
	v_mfma_i32_16x16x64_i8 v[8:11], v[172:175], v[196:199], v[8:11]
	v_mfma_i32_16x16x64_i8 v[4:7], v[164:167], v[204:207], v[4:7]
	v_mfma_i32_16x16x64_i8 v[0:3], v[172:175], v[204:207], v[0:3]
	v_mfma_i32_16x16x64_i8 v[28:31], v[168:171], v[184:187], v[28:31]
	v_mfma_i32_16x16x64_i8 v[24:27], v[176:179], v[184:187], v[24:27]
	v_mfma_i32_16x16x64_i8 v[20:23], v[168:171], v[192:195], v[20:23]
	v_mfma_i32_16x16x64_i8 v[16:19], v[176:179], v[192:195], v[16:19]
	v_mfma_i32_16x16x64_i8 v[12:15], v[168:171], v[200:203], v[12:15]
	v_mfma_i32_16x16x64_i8 v[8:11], v[176:179], v[200:203], v[8:11]
	v_mfma_i32_16x16x64_i8 v[4:7], v[168:171], v[208:211], v[4:7]
	v_mfma_i32_16x16x64_i8 v[0:3], v[176:179], v[208:211], v[0:3]
	s_setprio 0
	s_barrier
	ds_read_b128 v[132:135], v158
	ds_read_b128 v[136:139], v158 offset:1024
	ds_read_b128 v[140:143], v158 offset:2048
	ds_read_b128 v[160:163], v158 offset:3072
	ds_read_b128 v[164:167], v159
	ds_read_b128 v[168:171], v159 offset:1024
	ds_read_b128 v[172:175], v159 offset:2048
	ds_read_b128 v[176:179], v159 offset:3072
	ds_read_b128 v[180:183], v157 offset:32768
	ds_read_b128 v[184:187], v157 offset:33792
	ds_read_b128 v[188:191], v157 offset:34816
	ds_read_b128 v[192:195], v157 offset:35840
	ds_read_b128 v[196:199], v157 offset:36864
	ds_read_b128 v[200:203], v157 offset:37888
	ds_read_b128 v[204:207], v157 offset:38912
	ds_read_b128 v[208:211], v157 offset:39936
	s_add_u32 s36, s36, 0x4000
	s_addc_u32 s37, s37, 0
	s_mov_b32 m0, s66
	s_nop 0
	global_load_lds_dwordx4 v151, s[36:37]
	s_nop 0
	s_mov_b32 m0, s67
	s_nop 0
	global_load_lds_dwordx4 v153, s[36:37]
	s_waitcnt vmcnt(8)
	s_waitcnt lgkmcnt(0)
	s_setprio 1
	s_barrier
	v_mfma_i32_16x16x64_i8 v[124:127], v[132:135], v[180:183], v[124:127]
	v_mfma_i32_16x16x64_i8 v[120:123], v[140:143], v[180:183], v[120:123]
	v_mfma_i32_16x16x64_i8 v[116:119], v[132:135], v[188:191], v[116:119]
	v_mfma_i32_16x16x64_i8 v[112:115], v[140:143], v[188:191], v[112:115]
	v_mfma_i32_16x16x64_i8 v[108:111], v[132:135], v[196:199], v[108:111]
	v_mfma_i32_16x16x64_i8 v[104:107], v[140:143], v[196:199], v[104:107]
	v_mfma_i32_16x16x64_i8 v[100:103], v[132:135], v[204:207], v[100:103]
	v_mfma_i32_16x16x64_i8 v[96:99], v[140:143], v[204:207], v[96:99]
	v_mfma_i32_16x16x64_i8 v[124:127], v[136:139], v[184:187], v[124:127]
	v_mfma_i32_16x16x64_i8 v[120:123], v[160:163], v[184:187], v[120:123]
	v_mfma_i32_16x16x64_i8 v[116:119], v[136:139], v[192:195], v[116:119]
	v_mfma_i32_16x16x64_i8 v[112:115], v[160:163], v[192:195], v[112:115]
	v_mfma_i32_16x16x64_i8 v[108:111], v[136:139], v[200:203], v[108:111]
	v_mfma_i32_16x16x64_i8 v[104:107], v[160:163], v[200:203], v[104:107]
	v_mfma_i32_16x16x64_i8 v[100:103], v[136:139], v[208:211], v[100:103]
	v_mfma_i32_16x16x64_i8 v[96:99], v[160:163], v[208:211], v[96:99]
	s_setprio 0
	s_setprio 1
	v_mfma_i32_16x16x64_i8 v[92:95], v[164:167], v[180:183], v[92:95]
	v_mfma_i32_16x16x64_i8 v[88:91], v[172:175], v[180:183], v[88:91]
	v_mfma_i32_16x16x64_i8 v[84:87], v[164:167], v[188:191], v[84:87]
	v_mfma_i32_16x16x64_i8 v[80:83], v[172:175], v[188:191], v[80:83]
	v_mfma_i32_16x16x64_i8 v[76:79], v[164:167], v[196:199], v[76:79]
	v_mfma_i32_16x16x64_i8 v[72:75], v[172:175], v[196:199], v[72:75]
	v_mfma_i32_16x16x64_i8 v[68:71], v[164:167], v[204:207], v[68:71]
	v_mfma_i32_16x16x64_i8 v[64:67], v[172:175], v[204:207], v[64:67]
	v_mfma_i32_16x16x64_i8 v[92:95], v[168:171], v[184:187], v[92:95]
	v_mfma_i32_16x16x64_i8 v[88:91], v[176:179], v[184:187], v[88:91]
	v_mfma_i32_16x16x64_i8 v[84:87], v[168:171], v[192:195], v[84:87]
	v_mfma_i32_16x16x64_i8 v[80:83], v[176:179], v[192:195], v[80:83]
	v_mfma_i32_16x16x64_i8 v[76:79], v[168:171], v[200:203], v[76:79]
	v_mfma_i32_16x16x64_i8 v[72:75], v[176:179], v[200:203], v[72:75]
	v_mfma_i32_16x16x64_i8 v[68:71], v[168:171], v[208:211], v[68:71]
	v_mfma_i32_16x16x64_i8 v[64:67], v[176:179], v[208:211], v[64:67]
	s_setprio 0
	s_barrier
	ds_read_b128 v[180:183], v157 offset:49152
	ds_read_b128 v[184:187], v157 offset:50176
	ds_read_b128 v[188:191], v157 offset:51200
	ds_read_b128 v[192:195], v157 offset:52224
	ds_read_b128 v[196:199], v157 offset:53248
	ds_read_b128 v[200:203], v157 offset:54272
	ds_read_b128 v[204:207], v157 offset:55296
	ds_read_b128 v[208:211], v157 offset:56320
	s_add_u32 s36, s34, 0x8000
	s_addc_u32 s37, s35, 0
	s_mov_b32 m0, s68
	s_nop 0
	global_load_lds_dwordx4 v152, s[36:37]
	s_add_u32 s34, s34, 0xc000
	s_mov_b32 m0, s69
	s_nop 0
	global_load_lds_dwordx4 v154, s[36:37]
	s_addc_u32 s35, s35, 0
	s_mov_b32 m0, s72
	s_nop 0
	global_load_lds_dwordx4 v152, s[34:35]
	s_nop 0
	s_mov_b32 m0, s73
	s_nop 0
	global_load_lds_dwordx4 v154, s[34:35]
	s_nop 0
	s_mov_b32 m0, s70
	s_nop 0
	global_load_lds_dwordx4 v151, s[30:31]
	s_nop 0
	s_mov_b32 m0, s71
	s_nop 0
	global_load_lds_dwordx4 v153, s[30:31]
	s_waitcnt vmcnt(8)
	s_waitcnt lgkmcnt(0)
	s_setprio 1
	s_barrier
	v_mfma_i32_16x16x64_i8 v[60:63], v[132:135], v[180:183], v[60:63]
	v_mfma_i32_16x16x64_i8 v[56:59], v[140:143], v[180:183], v[56:59]
	v_mfma_i32_16x16x64_i8 v[52:55], v[132:135], v[188:191], v[52:55]
	v_mfma_i32_16x16x64_i8 v[48:51], v[140:143], v[188:191], v[48:51]
	v_mfma_i32_16x16x64_i8 v[44:47], v[132:135], v[196:199], v[44:47]
	v_mfma_i32_16x16x64_i8 v[40:43], v[140:143], v[196:199], v[40:43]
	v_mfma_i32_16x16x64_i8 v[36:39], v[132:135], v[204:207], v[36:39]
	v_mfma_i32_16x16x64_i8 v[32:35], v[140:143], v[204:207], v[32:35]
	v_mfma_i32_16x16x64_i8 v[60:63], v[136:139], v[184:187], v[60:63]
	v_mfma_i32_16x16x64_i8 v[56:59], v[160:163], v[184:187], v[56:59]
	v_mfma_i32_16x16x64_i8 v[52:55], v[136:139], v[192:195], v[52:55]
	v_mfma_i32_16x16x64_i8 v[48:51], v[160:163], v[192:195], v[48:51]
	v_mfma_i32_16x16x64_i8 v[44:47], v[136:139], v[200:203], v[44:47]
	v_mfma_i32_16x16x64_i8 v[40:43], v[160:163], v[200:203], v[40:43]
	v_mfma_i32_16x16x64_i8 v[36:39], v[136:139], v[208:211], v[36:39]
	v_mfma_i32_16x16x64_i8 v[32:35], v[160:163], v[208:211], v[32:35]
	s_setprio 0
	s_setprio 1
	v_mfma_i32_16x16x64_i8 v[28:31], v[164:167], v[180:183], v[28:31]
	v_mfma_i32_16x16x64_i8 v[24:27], v[172:175], v[180:183], v[24:27]
	v_mfma_i32_16x16x64_i8 v[20:23], v[164:167], v[188:191], v[20:23]
	v_mfma_i32_16x16x64_i8 v[16:19], v[172:175], v[188:191], v[16:19]
	v_mfma_i32_16x16x64_i8 v[12:15], v[164:167], v[196:199], v[12:15]
	v_mfma_i32_16x16x64_i8 v[8:11], v[172:175], v[196:199], v[8:11]
	v_mfma_i32_16x16x64_i8 v[4:7], v[164:167], v[204:207], v[4:7]
	v_mfma_i32_16x16x64_i8 v[0:3], v[172:175], v[204:207], v[0:3]
	v_mfma_i32_16x16x64_i8 v[28:31], v[168:171], v[184:187], v[28:31]
	v_mfma_i32_16x16x64_i8 v[24:27], v[176:179], v[184:187], v[24:27]
	v_mfma_i32_16x16x64_i8 v[20:23], v[168:171], v[192:195], v[20:23]
	v_mfma_i32_16x16x64_i8 v[16:19], v[176:179], v[192:195], v[16:19]
	v_mfma_i32_16x16x64_i8 v[12:15], v[168:171], v[200:203], v[12:15]
	v_mfma_i32_16x16x64_i8 v[8:11], v[176:179], v[200:203], v[8:11]
	v_mfma_i32_16x16x64_i8 v[4:7], v[168:171], v[208:211], v[4:7]
	v_mfma_i32_16x16x64_i8 v[0:3], v[176:179], v[208:211], v[0:3]
	s_setprio 0
	s_barrier
	s_add_i32 s82, s82, 2
	s_add_u32 s78, s78, 0x10000
	s_addc_u32 s79, s79, 0
	s_add_u32 s80, s80, 0x10000
	s_addc_u32 s81, s81, 0
	s_cmp_gt_u32 s82, 29
	s_cbranch_scc0 .LBB0_129
	s_and_b64 vcc, exec, s[14:15]
	s_cbranch_vccz .LBB0_132
	s_barrier

.LBB0_413:
	v_add_u32_e32 v0, 0x10000, v147
	ds_read_b128 v[134:137], v0
	ds_read_b128 v[138:141], v0 offset:1024
	ds_read_b128 v[150:153], v0 offset:2048
	ds_read_b128 v[154:157], v0 offset:3072
	v_add_u32_e32 v0, 0x14000, v147
	ds_read_b128 v[158:161], v0
	ds_read_b128 v[162:165], v0 offset:1024
	ds_read_b128 v[166:169], v0 offset:2048
	ds_read_b128 v[170:173], v0 offset:3072
	s_cmp_eq_u32 vcc_lo, 28
	s_cselect_b32 s54, s57, s93
	s_cselect_b32 s55, s56, s94
	s_cselect_b32 s8, s92, s95
	s_cselect_b32 s9, s47, s97
	s_add_u32 s6, s54, 0x8000
	s_addc_u32 s7, s55, 0
	ds_read_b128 v[174:177], v148
	ds_read_b128 v[178:181], v148 offset:1024
	ds_read_b128 v[182:185], v148 offset:2048
	ds_read_b128 v[186:189], v148 offset:3072
	ds_read_b128 v[190:193], v148 offset:4096
	ds_read_b128 v[194:197], v148 offset:5120
	ds_read_b128 v[198:201], v148 offset:6144
	ds_read_b128 v[202:205], v148 offset:7168
	s_add_u32 s0, s93, 0xffffc000
	s_addc_u32 s1, s94, -1
	s_mov_b32 m0, s90
	s_nop 0
	global_load_lds_dwordx4 v145, s[0:1]
	s_nop 0
	s_mov_b32 m0, s91
	s_nop 0
	global_load_lds_dwordx4 v146, s[0:1]
	s_waitcnt vmcnt(8)
	s_waitcnt lgkmcnt(0)
	s_setprio 1
	s_barrier
	v_mfma_f32_16x16x128_f8f6f4 v[206:209], v[134:141], v[174:181], v[206:209]
	v_mfma_f32_16x16x128_f8f6f4 v[210:213], v[150:157], v[174:181], v[210:213]
	v_mfma_f32_16x16x128_f8f6f4 v[32:35], v[134:141], v[190:197], v[32:35]
	v_mfma_f32_16x16x128_f8f6f4 v[36:39], v[150:157], v[190:197], v[36:39]
	v_mfma_f32_16x16x128_f8f6f4 v[48:51], v[134:141], v[198:205], v[48:51]
	v_mfma_f32_16x16x128_f8f6f4 v[52:55], v[150:157], v[198:205], v[52:55]
	v_mfma_f32_16x16x128_f8f6f4 v[214:217], v[134:141], v[182:189], v[16:19]
	v_mfma_f32_16x16x128_f8f6f4 v[218:221], v[150:157], v[182:189], v[20:23]
	s_setprio 0
	s_setprio 1
	v_mfma_f32_16x16x128_f8f6f4 v[222:225], v[158:165], v[174:181], v[8:11]
	v_mfma_f32_16x16x128_f8f6f4 v[174:177], v[166:173], v[174:181], v[12:15]
	v_mfma_f32_16x16x128_f8f6f4 v[178:181], v[158:165], v[182:189], v[24:27]
	v_mfma_f32_16x16x128_f8f6f4 v[182:185], v[166:173], v[182:189], v[28:31]
	v_mfma_f32_16x16x128_f8f6f4 v[186:189], v[158:165], v[190:197], v[40:43]
	v_mfma_f32_16x16x128_f8f6f4 v[190:193], v[166:173], v[190:197], v[44:47]
	v_mfma_f32_16x16x128_f8f6f4 v[194:197], v[158:165], v[198:205], v[56:59]
	v_mfma_f32_16x16x128_f8f6f4 v[198:201], v[166:173], v[198:205], v[60:63]
	s_setprio 0
	s_barrier
	ds_read_b128 v[0:3], v148 offset:16384
	ds_read_b128 v[4:7], v148 offset:17408
	ds_read_b128 v[8:11], v148 offset:18432
	ds_read_b128 v[12:15], v148 offset:19456
	ds_read_b128 v[16:19], v148 offset:20480
	ds_read_b128 v[20:23], v148 offset:21504
	ds_read_b128 v[24:27], v148 offset:22528
	ds_read_b128 v[28:31], v148 offset:23552
	s_mov_b32 m0, s76
	s_nop 0
	global_load_lds_dwordx4 v145, s[8:9]
	s_add_u32 s0, s8, 0x4000
	s_mov_b32 m0, s77
	s_nop 0
	global_load_lds_dwordx4 v146, s[8:9]
	s_addc_u32 s1, s9, 0
	s_mov_b32 m0, s78
	s_nop 0
	global_load_lds_dwordx4 v145, s[0:1]
	s_nop 0
	s_mov_b32 m0, s79
	s_nop 0
	global_load_lds_dwordx4 v146, s[0:1]
	s_nop 0
	s_mov_b32 m0, s75
	s_nop 0
	global_load_lds_dwordx4 v145, s[54:55]
	s_nop 0
	s_mov_b32 m0, s80
	s_nop 0
	global_load_lds_dwordx4 v146, s[54:55]
	s_waitcnt vmcnt(8)
	s_waitcnt lgkmcnt(0)
	s_setprio 1
	s_barrier
	v_mfma_f32_16x16x128_f8f6f4 v[80:83], v[134:141], v[8:15], v[80:83]
	v_mfma_f32_16x16x128_f8f6f4 v[84:87], v[150:157], v[8:15], v[84:87]
	v_mfma_f32_16x16x128_f8f6f4 v[96:99], v[134:141], v[16:23], v[96:99]
	v_mfma_f32_16x16x128_f8f6f4 v[100:103], v[150:157], v[16:23], v[100:103]
	v_mfma_f32_16x16x128_f8f6f4 v[124:127], v[134:141], v[24:31], v[124:127]
	v_mfma_f32_16x16x128_f8f6f4 v[120:123], v[150:157], v[24:31], v[120:123]
	v_mfma_f32_16x16x128_f8f6f4 v[202:205], v[134:141], v[0:7], v[64:67]
	v_mfma_f32_16x16x128_f8f6f4 v[226:229], v[150:157], v[0:7], v[68:71]
	s_setprio 0
	s_setprio 1
	v_mfma_f32_16x16x128_f8f6f4 v[230:233], v[158:165], v[0:7], v[72:75]
	v_mfma_f32_16x16x128_f8f6f4 v[234:237], v[166:173], v[0:7], v[76:79]
	v_mfma_f32_16x16x128_f8f6f4 v[238:241], v[158:165], v[8:15], v[88:91]
	v_mfma_f32_16x16x128_f8f6f4 v[242:245], v[166:173], v[8:15], v[92:95]
	v_mfma_f32_16x16x128_f8f6f4 v[246:249], v[158:165], v[16:23], v[104:107]
	v_mfma_f32_16x16x128_f8f6f4 v[130:133], v[166:173], v[16:23], v[108:111]
	v_mfma_f32_16x16x128_f8f6f4 v[0:3], v[158:165], v[24:31], v[116:119]
	v_mfma_f32_16x16x128_f8f6f4 v[4:7], v[166:173], v[24:31], v[112:115]
	s_setprio 0
	s_barrier
	v_add_u32_e32 v8, 0x18000, v147
	ds_read_b128 v[72:75], v8
	ds_read_b128 v[76:79], v8 offset:1024
	ds_read_b128 v[88:91], v8 offset:2048
	ds_read_b128 v[92:95], v8 offset:3072
	v_add_u32_e32 v8, 0x1c000, v147
	ds_read_b128 v[112:115], v8
	ds_read_b128 v[116:119], v8 offset:1024
	ds_read_b128 v[134:137], v8 offset:2048
	ds_read_b128 v[138:141], v8 offset:3072
	ds_read_b128 v[24:27], v148 offset:32768
	ds_read_b128 v[28:31], v148 offset:33792
	ds_read_b128 v[40:43], v148 offset:34816
	ds_read_b128 v[44:47], v148 offset:35840
	ds_read_b128 v[56:59], v148 offset:36864
	ds_read_b128 v[60:63], v148 offset:37888
	ds_read_b128 v[64:67], v148 offset:38912
	ds_read_b128 v[68:71], v148 offset:39936
	s_add_u32 s0, s54, 0x4000
	s_addc_u32 s1, s55, 0
	s_mov_b32 m0, s81
	s_nop 0
	global_load_lds_dwordx4 v145, s[0:1]
	s_nop 0
	s_mov_b32 m0, s82
	s_nop 0
	global_load_lds_dwordx4 v146, s[0:1]
	s_waitcnt vmcnt(8)
	s_waitcnt lgkmcnt(0)
	s_setprio 1
	s_barrier
	v_mfma_f32_16x16x128_f8f6f4 v[206:209], v[72:79], v[24:31], v[206:209]
	v_mfma_f32_16x16x128_f8f6f4 v[210:213], v[88:95], v[24:31], v[210:213]
	v_mfma_f32_16x16x128_f8f6f4 v[16:19], v[72:79], v[40:47], v[214:217]
	v_mfma_f32_16x16x128_f8f6f4 v[20:23], v[88:95], v[40:47], v[218:221]
	v_mfma_f32_16x16x128_f8f6f4 v[32:35], v[72:79], v[56:63], v[32:35]
	v_mfma_f32_16x16x128_f8f6f4 v[36:39], v[88:95], v[56:63], v[36:39]
	v_mfma_f32_16x16x128_f8f6f4 v[48:51], v[72:79], v[64:71], v[48:51]
	v_mfma_f32_16x16x128_f8f6f4 v[52:55], v[88:95], v[64:71], v[52:55]
	s_setprio 0
	s_setprio 1
	v_mfma_f32_16x16x128_f8f6f4 v[8:11], v[112:119], v[24:31], v[222:225]
	v_mfma_f32_16x16x128_f8f6f4 v[12:15], v[134:141], v[24:31], v[174:177]
	v_mfma_f32_16x16x128_f8f6f4 v[24:27], v[112:119], v[40:47], v[178:181]
	v_mfma_f32_16x16x128_f8f6f4 v[28:31], v[134:141], v[40:47], v[182:185]
	v_mfma_f32_16x16x128_f8f6f4 v[40:43], v[112:119], v[56:63], v[186:189]
	v_mfma_f32_16x16x128_f8f6f4 v[44:47], v[134:141], v[56:63], v[190:193]
	v_mfma_f32_16x16x128_f8f6f4 v[56:59], v[112:119], v[64:71], v[194:197]
	v_mfma_f32_16x16x128_f8f6f4 v[60:63], v[134:141], v[64:71], v[198:201]
	s_setprio 0
	s_barrier
	ds_read_b128 v[104:107], v148 offset:49152
	ds_read_b128 v[108:111], v148 offset:50176
	ds_read_b128 v[150:153], v148 offset:51200
	ds_read_b128 v[154:157], v148 offset:52224
	ds_read_b128 v[158:161], v148 offset:53248
	ds_read_b128 v[162:165], v148 offset:54272
	ds_read_b128 v[166:169], v148 offset:55296
	ds_read_b128 v[170:173], v148 offset:56320
	s_add_u32 s0, s8, 0x8000
	s_addc_u32 s1, s9, 0
	s_mov_b32 m0, s84
	s_nop 0
	global_load_lds_dwordx4 v145, s[0:1]
	s_nop 0
	s_mov_b32 m0, s85
	s_nop 0
	global_load_lds_dwordx4 v146, s[0:1]
	s_add_u32 s0, s8, 0xc000
	s_addc_u32 s1, s9, 0
	s_mov_b32 m0, s88
	s_nop 0
	global_load_lds_dwordx4 v145, s[0:1]
	s_nop 0
	s_mov_b32 m0, s89
	s_nop 0
	global_load_lds_dwordx4 v146, s[0:1]
	s_nop 0
	s_mov_b32 m0, s86
	s_nop 0
	global_load_lds_dwordx4 v145, s[6:7]
	s_nop 0
	s_mov_b32 m0, s87
	s_nop 0
	global_load_lds_dwordx4 v146, s[6:7]
	s_waitcnt vmcnt(8)
	s_waitcnt lgkmcnt(0)
	s_setprio 1
	s_barrier
	v_mfma_f32_16x16x128_f8f6f4 v[64:67], v[72:79], v[104:111], v[202:205]
	v_mfma_f32_16x16x128_f8f6f4 v[68:71], v[88:95], v[104:111], v[226:229]
	v_mfma_f32_16x16x128_f8f6f4 v[80:83], v[72:79], v[150:157], v[80:83]
	v_mfma_f32_16x16x128_f8f6f4 v[84:87], v[88:95], v[150:157], v[84:87]
	v_mfma_f32_16x16x128_f8f6f4 v[96:99], v[72:79], v[158:165], v[96:99]
	v_mfma_f32_16x16x128_f8f6f4 v[100:103], v[88:95], v[158:165], v[100:103]
	v_mfma_f32_16x16x128_f8f6f4 v[124:127], v[72:79], v[166:173], v[124:127]
	v_mfma_f32_16x16x128_f8f6f4 v[120:123], v[88:95], v[166:173], v[120:123]
	s_setprio 0
	s_setprio 1
	v_mfma_f32_16x16x128_f8f6f4 v[72:75], v[112:119], v[104:111], v[230:233]
	v_mfma_f32_16x16x128_f8f6f4 v[76:79], v[134:141], v[104:111], v[234:237]
	v_mfma_f32_16x16x128_f8f6f4 v[88:91], v[112:119], v[150:157], v[238:241]
	v_mfma_f32_16x16x128_f8f6f4 v[92:95], v[134:141], v[150:157], v[242:245]
	v_mfma_f32_16x16x128_f8f6f4 v[104:107], v[112:119], v[158:165], v[246:249]
	v_mfma_f32_16x16x128_f8f6f4 v[108:111], v[134:141], v[158:165], v[130:133]
	v_mfma_f32_16x16x128_f8f6f4 v[116:119], v[112:119], v[166:173], v[0:3]
	v_mfma_f32_16x16x128_f8f6f4 v[112:115], v[134:141], v[166:173], v[4:7]
	s_setprio 0
	s_barrier
	s_add_i32 vcc_lo, vcc_lo, 2
	s_add_u32 s93, s93, 0x10000
	s_addc_u32 s94, s94, 0
	s_add_u32 s95, s95, 0x10000
	s_addc_u32 s97, s97, 0
	s_cmp_gt_u32 vcc_lo, 29
	s_cbranch_scc0 .LBB0_413
	s_and_b64 vcc, exec, s[34:35]
	s_cbranch_vccz .LBB0_416
	s_barrier

.LBB0_535:
	ds_read_b128 v[150:153], v128
	ds_read_b128 v[154:157], v128 offset:1024
	ds_read_b128 v[158:161], v128 offset:2048
	ds_read_b128 v[170:173], v128 offset:3072
	ds_read_b128 v[174:177], v146
	ds_read_b128 v[178:181], v146 offset:1024
	ds_read_b128 v[182:185], v146 offset:2048
	ds_read_b128 v[186:189], v146 offset:3072
	s_cmp_eq_u32 s16, 60
	s_cselect_b32 s62, s94, vcc_lo
	s_cselect_b32 s63, s53, vcc_hi
	s_cselect_b32 s60, s95, s14
	s_cselect_b32 s61, s41, s15
	s_add_u32 s58, s62, 0x8000
	s_addc_u32 s59, s63, 0
	ds_read_b128 v[190:193], v147
	ds_read_b128 v[194:197], v147 offset:1024
	ds_read_b128 v[198:201], v147 offset:2048
	ds_read_b128 v[202:205], v147 offset:3072
	ds_read_b128 v[206:209], v147 offset:4096
	ds_read_b128 v[210:213], v147 offset:5120
	ds_read_b128 v[214:217], v147 offset:6144
	ds_read_b128 v[218:221], v147 offset:7168
	s_add_u32 s18, vcc_lo, 0xffffc000
	s_addc_u32 s19, vcc_hi, -1
	s_mov_b32 m0, s89
	s_nop 0
	global_load_lds_dwordx4 v142, s[18:19]
	s_nop 0
	s_mov_b32 m0, s90
	s_nop 0
	global_load_lds_dwordx4 v144, s[18:19]
	s_waitcnt vmcnt(8)
	s_waitcnt lgkmcnt(0)
	s_setprio 1
	s_barrier
	v_mfma_f32_16x16x32_bf16 v[124:127], v[150:153], v[190:193], v[124:127]
	v_mfma_f32_16x16x32_bf16 v[120:123], v[158:161], v[190:193], v[120:123]
	v_mfma_f32_16x16x32_bf16 v[108:111], v[150:153], v[198:201], v[108:111]
	v_mfma_f32_16x16x32_bf16 v[104:107], v[158:161], v[198:201], v[104:107]
	v_mfma_f32_16x16x32_bf16 v[92:95], v[150:153], v[206:209], v[92:95]
	v_mfma_f32_16x16x32_bf16 v[88:91], v[158:161], v[206:209], v[88:91]
	v_mfma_f32_16x16x32_bf16 v[76:79], v[150:153], v[214:217], v[76:79]
	v_mfma_f32_16x16x32_bf16 v[72:75], v[158:161], v[214:217], v[72:75]
	v_mfma_f32_16x16x32_bf16 v[124:127], v[154:157], v[194:197], v[124:127]
	v_mfma_f32_16x16x32_bf16 v[120:123], v[170:173], v[194:197], v[120:123]
	v_mfma_f32_16x16x32_bf16 v[108:111], v[154:157], v[202:205], v[108:111]
	v_mfma_f32_16x16x32_bf16 v[104:107], v[170:173], v[202:205], v[104:107]
	v_mfma_f32_16x16x32_bf16 v[92:95], v[154:157], v[210:213], v[92:95]
	v_mfma_f32_16x16x32_bf16 v[88:91], v[170:173], v[210:213], v[88:91]
	v_mfma_f32_16x16x32_bf16 v[76:79], v[154:157], v[218:221], v[76:79]
	v_mfma_f32_16x16x32_bf16 v[72:75], v[170:173], v[218:221], v[72:75]
	s_setprio 0
	s_setprio 1
	v_mfma_f32_16x16x32_bf16 v[116:119], v[174:177], v[190:193], v[116:119]
	v_mfma_f32_16x16x32_bf16 v[112:115], v[182:185], v[190:193], v[112:115]
	v_mfma_f32_16x16x32_bf16 v[100:103], v[174:177], v[198:201], v[100:103]
	v_mfma_f32_16x16x32_bf16 v[96:99], v[182:185], v[198:201], v[96:99]
	v_mfma_f32_16x16x32_bf16 v[84:87], v[174:177], v[206:209], v[84:87]
	v_mfma_f32_16x16x32_bf16 v[80:83], v[182:185], v[206:209], v[80:83]
	v_mfma_f32_16x16x32_bf16 v[68:71], v[174:177], v[214:217], v[68:71]
	v_mfma_f32_16x16x32_bf16 v[64:67], v[182:185], v[214:217], v[64:67]
	v_mfma_f32_16x16x32_bf16 v[116:119], v[178:181], v[194:197], v[116:119]
	v_mfma_f32_16x16x32_bf16 v[112:115], v[186:189], v[194:197], v[112:115]
	v_mfma_f32_16x16x32_bf16 v[100:103], v[178:181], v[202:205], v[100:103]
	v_mfma_f32_16x16x32_bf16 v[96:99], v[186:189], v[202:205], v[96:99]
	v_mfma_f32_16x16x32_bf16 v[84:87], v[178:181], v[210:213], v[84:87]
	v_mfma_f32_16x16x32_bf16 v[80:83], v[186:189], v[210:213], v[80:83]
	v_mfma_f32_16x16x32_bf16 v[68:71], v[178:181], v[218:221], v[68:71]
	v_mfma_f32_16x16x32_bf16 v[64:67], v[186:189], v[218:221], v[64:67]
	s_setprio 0
	s_barrier
	ds_read_b128 v[190:193], v147 offset:16384
	ds_read_b128 v[194:197], v147 offset:17408
	ds_read_b128 v[198:201], v147 offset:18432
	ds_read_b128 v[202:205], v147 offset:19456
	ds_read_b128 v[206:209], v147 offset:20480
	ds_read_b128 v[210:213], v147 offset:21504
	ds_read_b128 v[214:217], v147 offset:22528
	ds_read_b128 v[218:221], v147 offset:23552
	s_mov_b32 m0, s45
	s_nop 0
	global_load_lds_dwordx4 v143, s[60:61]
	s_add_u32 s18, s60, 0x4000
	s_mov_b32 m0, s46
	s_nop 0
	global_load_lds_dwordx4 v145, s[60:61]
	s_addc_u32 s19, s61, 0
	s_mov_b32 m0, s47
	s_nop 0
	global_load_lds_dwordx4 v143, s[18:19]
	s_nop 0
	s_mov_b32 m0, s64
	s_nop 0
	global_load_lds_dwordx4 v145, s[18:19]
	s_nop 0
	s_mov_b32 m0, s44
	s_nop 0
	global_load_lds_dwordx4 v142, s[62:63]
	s_nop 0
	s_mov_b32 m0, s65
	s_nop 0
	global_load_lds_dwordx4 v144, s[62:63]
	s_waitcnt vmcnt(8)
	s_waitcnt lgkmcnt(0)
	s_setprio 1
	s_barrier
	v_mfma_f32_16x16x32_bf16 v[60:63], v[150:153], v[190:193], v[60:63]
	v_mfma_f32_16x16x32_bf16 v[56:59], v[158:161], v[190:193], v[56:59]
	v_mfma_f32_16x16x32_bf16 v[44:47], v[150:153], v[198:201], v[44:47]
	v_mfma_f32_16x16x32_bf16 v[40:43], v[158:161], v[198:201], v[40:43]
	v_mfma_f32_16x16x32_bf16 v[28:31], v[150:153], v[206:209], v[28:31]
	v_mfma_f32_16x16x32_bf16 v[24:27], v[158:161], v[206:209], v[24:27]
	v_mfma_f32_16x16x32_bf16 v[12:15], v[150:153], v[214:217], v[12:15]
	v_mfma_f32_16x16x32_bf16 v[8:11], v[158:161], v[214:217], v[8:11]
	v_mfma_f32_16x16x32_bf16 v[60:63], v[154:157], v[194:197], v[60:63]
	v_mfma_f32_16x16x32_bf16 v[56:59], v[170:173], v[194:197], v[56:59]
	v_mfma_f32_16x16x32_bf16 v[44:47], v[154:157], v[202:205], v[44:47]
	v_mfma_f32_16x16x32_bf16 v[40:43], v[170:173], v[202:205], v[40:43]
	v_mfma_f32_16x16x32_bf16 v[28:31], v[154:157], v[210:213], v[28:31]
	v_mfma_f32_16x16x32_bf16 v[24:27], v[170:173], v[210:213], v[24:27]
	v_mfma_f32_16x16x32_bf16 v[12:15], v[154:157], v[218:221], v[12:15]
	v_mfma_f32_16x16x32_bf16 v[8:11], v[170:173], v[218:221], v[8:11]
	s_setprio 0
	s_setprio 1
	v_mfma_f32_16x16x32_bf16 v[52:55], v[174:177], v[190:193], v[52:55]
	v_mfma_f32_16x16x32_bf16 v[48:51], v[182:185], v[190:193], v[48:51]
	v_mfma_f32_16x16x32_bf16 v[36:39], v[174:177], v[198:201], v[36:39]
	v_mfma_f32_16x16x32_bf16 v[32:35], v[182:185], v[198:201], v[32:35]
	v_mfma_f32_16x16x32_bf16 v[20:23], v[174:177], v[206:209], v[20:23]
	v_mfma_f32_16x16x32_bf16 v[16:19], v[182:185], v[206:209], v[16:19]
	v_mfma_f32_16x16x32_bf16 v[4:7], v[174:177], v[214:217], v[4:7]
	v_mfma_f32_16x16x32_bf16 v[0:3], v[182:185], v[214:217], v[0:3]
	v_mfma_f32_16x16x32_bf16 v[52:55], v[178:181], v[194:197], v[52:55]
	v_mfma_f32_16x16x32_bf16 v[48:51], v[186:189], v[194:197], v[48:51]
	v_mfma_f32_16x16x32_bf16 v[36:39], v[178:181], v[202:205], v[36:39]
	v_mfma_f32_16x16x32_bf16 v[32:35], v[186:189], v[202:205], v[32:35]
	v_mfma_f32_16x16x32_bf16 v[20:23], v[178:181], v[210:213], v[20:23]
	v_mfma_f32_16x16x32_bf16 v[16:19], v[186:189], v[210:213], v[16:19]
	v_mfma_f32_16x16x32_bf16 v[4:7], v[178:181], v[218:221], v[4:7]
	v_mfma_f32_16x16x32_bf16 v[0:3], v[186:189], v[218:221], v[0:3]
	s_setprio 0
	s_barrier
	ds_read_b128 v[150:153], v148
	ds_read_b128 v[154:157], v148 offset:1024
	ds_read_b128 v[158:161], v148 offset:2048
	ds_read_b128 v[170:173], v148 offset:3072
	ds_read_b128 v[174:177], v149
	ds_read_b128 v[178:181], v149 offset:1024
	ds_read_b128 v[182:185], v149 offset:2048
	ds_read_b128 v[186:189], v149 offset:3072
	ds_read_b128 v[190:193], v147 offset:32768
	ds_read_b128 v[194:197], v147 offset:33792
	ds_read_b128 v[198:201], v147 offset:34816
	ds_read_b128 v[202:205], v147 offset:35840
	ds_read_b128 v[206:209], v147 offset:36864
	ds_read_b128 v[210:213], v147 offset:37888
	ds_read_b128 v[214:217], v147 offset:38912
	ds_read_b128 v[218:221], v147 offset:39936
	s_add_u32 s18, s62, 0x4000
	s_addc_u32 s19, s63, 0
	s_mov_b32 m0, s66
	s_nop 0
	global_load_lds_dwordx4 v142, s[18:19]
	s_nop 0
	s_mov_b32 m0, s67
	s_nop 0
	global_load_lds_dwordx4 v144, s[18:19]
	s_waitcnt vmcnt(8)
	s_waitcnt lgkmcnt(0)
	s_setprio 1
	s_barrier
	v_mfma_f32_16x16x32_bf16 v[124:127], v[150:153], v[190:193], v[124:127]
	v_mfma_f32_16x16x32_bf16 v[120:123], v[158:161], v[190:193], v[120:123]
	v_mfma_f32_16x16x32_bf16 v[108:111], v[150:153], v[198:201], v[108:111]
	v_mfma_f32_16x16x32_bf16 v[104:107], v[158:161], v[198:201], v[104:107]
	v_mfma_f32_16x16x32_bf16 v[92:95], v[150:153], v[206:209], v[92:95]
	v_mfma_f32_16x16x32_bf16 v[88:91], v[158:161], v[206:209], v[88:91]
	v_mfma_f32_16x16x32_bf16 v[76:79], v[150:153], v[214:217], v[76:79]
	v_mfma_f32_16x16x32_bf16 v[72:75], v[158:161], v[214:217], v[72:75]
	v_mfma_f32_16x16x32_bf16 v[124:127], v[154:157], v[194:197], v[124:127]
	v_mfma_f32_16x16x32_bf16 v[120:123], v[170:173], v[194:197], v[120:123]
	v_mfma_f32_16x16x32_bf16 v[108:111], v[154:157], v[202:205], v[108:111]
	v_mfma_f32_16x16x32_bf16 v[104:107], v[170:173], v[202:205], v[104:107]
	v_mfma_f32_16x16x32_bf16 v[92:95], v[154:157], v[210:213], v[92:95]
	v_mfma_f32_16x16x32_bf16 v[88:91], v[170:173], v[210:213], v[88:91]
	v_mfma_f32_16x16x32_bf16 v[76:79], v[154:157], v[218:221], v[76:79]
	v_mfma_f32_16x16x32_bf16 v[72:75], v[170:173], v[218:221], v[72:75]
	s_setprio 0
	s_setprio 1
	v_mfma_f32_16x16x32_bf16 v[116:119], v[174:177], v[190:193], v[116:119]
	v_mfma_f32_16x16x32_bf16 v[112:115], v[182:185], v[190:193], v[112:115]
	v_mfma_f32_16x16x32_bf16 v[100:103], v[174:177], v[198:201], v[100:103]
	v_mfma_f32_16x16x32_bf16 v[96:99], v[182:185], v[198:201], v[96:99]
	v_mfma_f32_16x16x32_bf16 v[84:87], v[174:177], v[206:209], v[84:87]
	v_mfma_f32_16x16x32_bf16 v[80:83], v[182:185], v[206:209], v[80:83]
	v_mfma_f32_16x16x32_bf16 v[68:71], v[174:177], v[214:217], v[68:71]
	v_mfma_f32_16x16x32_bf16 v[64:67], v[182:185], v[214:217], v[64:67]
	v_mfma_f32_16x16x32_bf16 v[116:119], v[178:181], v[194:197], v[116:119]
	v_mfma_f32_16x16x32_bf16 v[112:115], v[186:189], v[194:197], v[112:115]
	v_mfma_f32_16x16x32_bf16 v[100:103], v[178:181], v[202:205], v[100:103]
	v_mfma_f32_16x16x32_bf16 v[96:99], v[186:189], v[202:205], v[96:99]
	v_mfma_f32_16x16x32_bf16 v[84:87], v[178:181], v[210:213], v[84:87]
	v_mfma_f32_16x16x32_bf16 v[80:83], v[186:189], v[210:213], v[80:83]
	v_mfma_f32_16x16x32_bf16 v[68:71], v[178:181], v[218:221], v[68:71]
	v_mfma_f32_16x16x32_bf16 v[64:67], v[186:189], v[218:221], v[64:67]
	s_setprio 0
	s_barrier
	ds_read_b128 v[190:193], v147 offset:49152
	ds_read_b128 v[194:197], v147 offset:50176
	ds_read_b128 v[198:201], v147 offset:51200
	ds_read_b128 v[202:205], v147 offset:52224
	ds_read_b128 v[206:209], v147 offset:53248
	ds_read_b128 v[210:213], v147 offset:54272
	ds_read_b128 v[214:217], v147 offset:55296
	ds_read_b128 v[218:221], v147 offset:56320
	s_add_u32 s18, s60, 0x8000
	s_addc_u32 s19, s61, 0
	s_mov_b32 m0, s70
	s_nop 0
	global_load_lds_dwordx4 v143, s[18:19]
	s_nop 0
	s_mov_b32 m0, s71
	s_nop 0
	global_load_lds_dwordx4 v145, s[18:19]
	s_add_u32 s18, s60, 0xc000
	s_addc_u32 s19, s61, 0
	s_mov_b32 m0, s83
	s_nop 0
	global_load_lds_dwordx4 v143, s[18:19]
	s_nop 0
	s_mov_b32 m0, s88
	s_nop 0
	global_load_lds_dwordx4 v145, s[18:19]
	s_nop 0
	s_mov_b32 m0, s72
	s_nop 0
	global_load_lds_dwordx4 v142, s[58:59]
	s_nop 0
	s_mov_b32 m0, s81
	s_nop 0
	global_load_lds_dwordx4 v144, s[58:59]
	s_waitcnt vmcnt(8)
	s_waitcnt lgkmcnt(0)
	s_setprio 1
	s_barrier
	v_mfma_f32_16x16x32_bf16 v[60:63], v[150:153], v[190:193], v[60:63]
	v_mfma_f32_16x16x32_bf16 v[56:59], v[158:161], v[190:193], v[56:59]
	v_mfma_f32_16x16x32_bf16 v[44:47], v[150:153], v[198:201], v[44:47]
	v_mfma_f32_16x16x32_bf16 v[40:43], v[158:161], v[198:201], v[40:43]
	v_mfma_f32_16x16x32_bf16 v[28:31], v[150:153], v[206:209], v[28:31]
	v_mfma_f32_16x16x32_bf16 v[24:27], v[158:161], v[206:209], v[24:27]
	v_mfma_f32_16x16x32_bf16 v[12:15], v[150:153], v[214:217], v[12:15]
	v_mfma_f32_16x16x32_bf16 v[8:11], v[158:161], v[214:217], v[8:11]
	v_mfma_f32_16x16x32_bf16 v[60:63], v[154:157], v[194:197], v[60:63]
	v_mfma_f32_16x16x32_bf16 v[56:59], v[170:173], v[194:197], v[56:59]
	v_mfma_f32_16x16x32_bf16 v[44:47], v[154:157], v[202:205], v[44:47]
	v_mfma_f32_16x16x32_bf16 v[40:43], v[170:173], v[202:205], v[40:43]
	v_mfma_f32_16x16x32_bf16 v[28:31], v[154:157], v[210:213], v[28:31]
	v_mfma_f32_16x16x32_bf16 v[24:27], v[170:173], v[210:213], v[24:27]
	v_mfma_f32_16x16x32_bf16 v[12:15], v[154:157], v[218:221], v[12:15]
	v_mfma_f32_16x16x32_bf16 v[8:11], v[170:173], v[218:221], v[8:11]
	s_setprio 0
	s_setprio 1
	v_mfma_f32_16x16x32_bf16 v[52:55], v[174:177], v[190:193], v[52:55]
	v_mfma_f32_16x16x32_bf16 v[48:51], v[182:185], v[190:193], v[48:51]
	v_mfma_f32_16x16x32_bf16 v[36:39], v[174:177], v[198:201], v[36:39]
	v_mfma_f32_16x16x32_bf16 v[32:35], v[182:185], v[198:201], v[32:35]
	v_mfma_f32_16x16x32_bf16 v[20:23], v[174:177], v[206:209], v[20:23]
	v_mfma_f32_16x16x32_bf16 v[16:19], v[182:185], v[206:209], v[16:19]
	v_mfma_f32_16x16x32_bf16 v[4:7], v[174:177], v[214:217], v[4:7]
	v_mfma_f32_16x16x32_bf16 v[0:3], v[182:185], v[214:217], v[0:3]
	v_mfma_f32_16x16x32_bf16 v[52:55], v[178:181], v[194:197], v[52:55]
	v_mfma_f32_16x16x32_bf16 v[48:51], v[186:189], v[194:197], v[48:51]
	v_mfma_f32_16x16x32_bf16 v[36:39], v[178:181], v[202:205], v[36:39]
	v_mfma_f32_16x16x32_bf16 v[32:35], v[186:189], v[202:205], v[32:35]
	v_mfma_f32_16x16x32_bf16 v[20:23], v[178:181], v[210:213], v[20:23]
	v_mfma_f32_16x16x32_bf16 v[16:19], v[186:189], v[210:213], v[16:19]
	v_mfma_f32_16x16x32_bf16 v[4:7], v[178:181], v[218:221], v[4:7]
	v_mfma_f32_16x16x32_bf16 v[0:3], v[186:189], v[218:221], v[0:3]
	s_setprio 0
	s_barrier
	s_add_i32 s16, s16, 2
	s_add_u32 vcc_lo, vcc_lo, 0x10000
	s_addc_u32 vcc_hi, vcc_hi, 0
	s_add_u32 s14, s14, 0x10000
	s_addc_u32 s15, s15, 0
	s_cmp_gt_u32 s16, 61
	s_cbranch_scc0 .LBB0_535
	s_and_b64 vcc, exec, s[48:49]
	s_cbranch_vccz .LBB0_538
	s_barrier

.LBB0_618:
	v_add_u32_e32 v164, 0x10000, v179
	ds_read_b128 v[182:185], v164
	ds_read_b128 v[186:189], v164 offset:1024
	ds_read_b128 v[190:193], v164 offset:2048
	ds_read_b128 v[194:197], v164 offset:3072
	v_add_u32_e32 v164, 0x14000, v179
	ds_read_b128 v[198:201], v164
	ds_read_b128 v[202:205], v164 offset:1024
	ds_read_b128 v[206:209], v164 offset:2048
	ds_read_b128 v[210:213], v164 offset:3072
	s_cmpk_eq_i32 s18, 0xfc
	s_cselect_b32 s66, s16, s55
	s_cselect_b32 s67, s15, s61
	s_cselect_b32 s64, s17, vcc_lo
	s_cselect_b32 s65, s11, vcc_hi
	s_add_u32 s62, s66, 0x8000
	s_addc_u32 s63, s67, 0
	ds_read_b128 v[214:217], v180
	ds_read_b128 v[218:221], v180 offset:1024
	ds_read_b128 v[222:225], v180 offset:2048
	ds_read_b128 v[226:229], v180 offset:3072
	ds_read_b128 v[230:233], v180 offset:4096
	ds_read_b128 v[234:237], v180 offset:5120
	ds_read_b128 v[238:241], v180 offset:6144
	ds_read_b128 v[242:245], v180 offset:7168
	s_add_u32 s28, s55, 0xffffc000
	s_addc_u32 s29, s61, -1
	s_mov_b32 m0, s47
	s_nop 0
	global_load_lds_dwordx4 v176, s[28:29]
	s_nop 0
	s_mov_b32 m0, s94
	s_nop 0
	global_load_lds_dwordx4 v177, s[28:29]
	s_waitcnt vmcnt(8)
	s_waitcnt lgkmcnt(0)
	s_setprio 1
	s_barrier
	v_mfma_f32_16x16x32_bf16 v[0:3], v[182:185], v[214:217], v[0:3]
	v_mfma_f32_16x16x32_bf16 v[4:7], v[190:193], v[214:217], v[4:7]
	v_mfma_f32_16x16x32_bf16 v[12:15], v[182:185], v[222:225], v[12:15]
	v_mfma_f32_16x16x32_bf16 v[24:27], v[190:193], v[222:225], v[24:27]
	v_mfma_f32_16x16x32_bf16 v[44:47], v[182:185], v[230:233], v[44:47]
	v_mfma_f32_16x16x32_bf16 v[56:59], v[190:193], v[230:233], v[56:59]
	v_mfma_f32_16x16x32_bf16 v[68:71], v[182:185], v[238:241], v[68:71]
	v_mfma_f32_16x16x32_bf16 v[80:83], v[190:193], v[238:241], v[80:83]
	v_mfma_f32_16x16x32_bf16 v[0:3], v[186:189], v[218:221], v[0:3]
	v_mfma_f32_16x16x32_bf16 v[4:7], v[194:197], v[218:221], v[4:7]
	v_mfma_f32_16x16x32_bf16 v[12:15], v[186:189], v[226:229], v[12:15]
	v_mfma_f32_16x16x32_bf16 v[24:27], v[194:197], v[226:229], v[24:27]
	v_mfma_f32_16x16x32_bf16 v[44:47], v[186:189], v[234:237], v[44:47]
	v_mfma_f32_16x16x32_bf16 v[56:59], v[194:197], v[234:237], v[56:59]
	v_mfma_f32_16x16x32_bf16 v[68:71], v[186:189], v[242:245], v[68:71]
	v_mfma_f32_16x16x32_bf16 v[80:83], v[194:197], v[242:245], v[80:83]
	s_setprio 0
	s_setprio 1
	v_mfma_f32_16x16x32_bf16 v[20:23], v[198:201], v[214:217], v[20:23]
	v_mfma_f32_16x16x32_bf16 v[36:39], v[206:209], v[214:217], v[36:39]
	v_mfma_f32_16x16x32_bf16 v[48:51], v[198:201], v[222:225], v[48:51]
	v_mfma_f32_16x16x32_bf16 v[60:63], v[206:209], v[222:225], v[60:63]
	v_mfma_f32_16x16x32_bf16 v[72:75], v[198:201], v[230:233], v[72:75]
	v_mfma_f32_16x16x32_bf16 v[88:91], v[206:209], v[230:233], v[88:91]
	v_mfma_f32_16x16x32_bf16 v[96:99], v[198:201], v[238:241], v[96:99]
	v_mfma_f32_16x16x32_bf16 v[104:107], v[206:209], v[238:241], v[104:107]
	v_mfma_f32_16x16x32_bf16 v[20:23], v[202:205], v[218:221], v[20:23]
	v_mfma_f32_16x16x32_bf16 v[36:39], v[210:213], v[218:221], v[36:39]
	v_mfma_f32_16x16x32_bf16 v[48:51], v[202:205], v[226:229], v[48:51]
	v_mfma_f32_16x16x32_bf16 v[60:63], v[210:213], v[226:229], v[60:63]
	v_mfma_f32_16x16x32_bf16 v[72:75], v[202:205], v[234:237], v[72:75]
	v_mfma_f32_16x16x32_bf16 v[88:91], v[210:213], v[234:237], v[88:91]
	v_mfma_f32_16x16x32_bf16 v[96:99], v[202:205], v[242:245], v[96:99]
	v_mfma_f32_16x16x32_bf16 v[104:107], v[210:213], v[242:245], v[104:107]
	s_setprio 0
	s_barrier
	ds_read_b128 v[214:217], v180 offset:16384
	ds_read_b128 v[218:221], v180 offset:17408
	ds_read_b128 v[222:225], v180 offset:18432
	ds_read_b128 v[226:229], v180 offset:19456
	ds_read_b128 v[230:233], v180 offset:20480
	ds_read_b128 v[234:237], v180 offset:21504
	ds_read_b128 v[238:241], v180 offset:22528
	ds_read_b128 v[242:245], v180 offset:23552
	s_mov_b32 m0, s8
	s_nop 0
	global_load_lds_dwordx4 v176, s[64:65]
	s_add_u32 s28, s64, 0x4000
	s_mov_b32 m0, s20
	s_nop 0
	global_load_lds_dwordx4 v177, s[64:65]
	s_addc_u32 s29, s65, 0
	s_mov_b32 m0, s22
	s_nop 0
	global_load_lds_dwordx4 v176, s[28:29]
	s_nop 0
	s_mov_b32 m0, s24
	s_nop 0
	global_load_lds_dwordx4 v177, s[28:29]
	s_nop 0
	s_mov_b32 m0, s83
	s_nop 0
	global_load_lds_dwordx4 v176, s[66:67]
	s_nop 0
	s_mov_b32 m0, s25
	s_nop 0
	global_load_lds_dwordx4 v177, s[66:67]
	s_waitcnt vmcnt(8)
	s_waitcnt lgkmcnt(0)
	s_setprio 1
	s_barrier
	v_mfma_f32_16x16x32_bf16 v[28:31], v[182:185], v[214:217], v[28:31]
	v_mfma_f32_16x16x32_bf16 v[8:11], v[190:193], v[214:217], v[8:11]
	v_mfma_f32_16x16x32_bf16 v[40:43], v[182:185], v[222:225], v[40:43]
	v_mfma_f32_16x16x32_bf16 v[52:55], v[190:193], v[222:225], v[52:55]
	v_mfma_f32_16x16x32_bf16 v[84:87], v[182:185], v[230:233], v[84:87]
	v_mfma_f32_16x16x32_bf16 v[92:95], v[190:193], v[230:233], v[92:95]
	v_mfma_f32_16x16x32_bf16 v[112:115], v[182:185], v[238:241], v[112:115]
	v_mfma_f32_16x16x32_bf16 v[116:119], v[190:193], v[238:241], v[116:119]
	v_mfma_f32_16x16x32_bf16 v[28:31], v[186:189], v[218:221], v[28:31]
	v_mfma_f32_16x16x32_bf16 v[8:11], v[194:197], v[218:221], v[8:11]
	v_mfma_f32_16x16x32_bf16 v[40:43], v[186:189], v[226:229], v[40:43]
	v_mfma_f32_16x16x32_bf16 v[52:55], v[194:197], v[226:229], v[52:55]
	v_mfma_f32_16x16x32_bf16 v[84:87], v[186:189], v[234:237], v[84:87]
	v_mfma_f32_16x16x32_bf16 v[92:95], v[194:197], v[234:237], v[92:95]
	v_mfma_f32_16x16x32_bf16 v[112:115], v[186:189], v[242:245], v[112:115]
	v_mfma_f32_16x16x32_bf16 v[116:119], v[194:197], v[242:245], v[116:119]
	s_setprio 0
	s_setprio 1
	v_mfma_f32_16x16x32_bf16 v[16:19], v[198:201], v[214:217], v[16:19]
	v_mfma_f32_16x16x32_bf16 v[32:35], v[206:209], v[214:217], v[32:35]
	v_mfma_f32_16x16x32_bf16 v[64:67], v[198:201], v[222:225], v[64:67]
	v_mfma_f32_16x16x32_bf16 v[76:79], v[206:209], v[222:225], v[76:79]
	v_mfma_f32_16x16x32_bf16 v[100:103], v[198:201], v[230:233], v[100:103]
	v_mfma_f32_16x16x32_bf16 v[108:111], v[206:209], v[230:233], v[108:111]
	v_mfma_f32_16x16x32_bf16 v[120:123], v[198:201], v[238:241], v[120:123]
	v_mfma_f32_16x16x32_bf16 v[124:127], v[206:209], v[238:241], v[124:127]
	v_mfma_f32_16x16x32_bf16 v[16:19], v[202:205], v[218:221], v[16:19]
	v_mfma_f32_16x16x32_bf16 v[32:35], v[210:213], v[218:221], v[32:35]
	v_mfma_f32_16x16x32_bf16 v[64:67], v[202:205], v[226:229], v[64:67]
	v_mfma_f32_16x16x32_bf16 v[76:79], v[210:213], v[226:229], v[76:79]
	v_mfma_f32_16x16x32_bf16 v[100:103], v[202:205], v[234:237], v[100:103]
	v_mfma_f32_16x16x32_bf16 v[108:111], v[210:213], v[234:237], v[108:111]
	v_mfma_f32_16x16x32_bf16 v[120:123], v[202:205], v[242:245], v[120:123]
	v_mfma_f32_16x16x32_bf16 v[124:127], v[210:213], v[242:245], v[124:127]
	s_setprio 0
	s_barrier
	v_add_u32_e32 v164, 0x18000, v179
	ds_read_b128 v[182:185], v164
	ds_read_b128 v[186:189], v164 offset:1024
	ds_read_b128 v[190:193], v164 offset:2048
	ds_read_b128 v[194:197], v164 offset:3072
	v_add_u32_e32 v164, 0x1c000, v179
	ds_read_b128 v[198:201], v164
	ds_read_b128 v[202:205], v164 offset:1024
	ds_read_b128 v[206:209], v164 offset:2048
	ds_read_b128 v[210:213], v164 offset:3072
	ds_read_b128 v[214:217], v180 offset:32768
	ds_read_b128 v[218:221], v180 offset:33792
	ds_read_b128 v[222:225], v180 offset:34816
	ds_read_b128 v[226:229], v180 offset:35840
	ds_read_b128 v[230:233], v180 offset:36864
	ds_read_b128 v[234:237], v180 offset:37888
	ds_read_b128 v[238:241], v180 offset:38912
	ds_read_b128 v[242:245], v180 offset:39936
	s_add_u32 s28, s66, 0x4000
	s_addc_u32 s29, s67, 0
	s_mov_b32 m0, s4
	s_nop 0
	global_load_lds_dwordx4 v176, s[28:29]
	s_nop 0
	s_mov_b32 m0, s5
	s_nop 0
	global_load_lds_dwordx4 v177, s[28:29]
	s_waitcnt vmcnt(8)
	s_waitcnt lgkmcnt(0)
	s_setprio 1
	s_barrier
	v_mfma_f32_16x16x32_bf16 v[0:3], v[182:185], v[214:217], v[0:3]
	v_mfma_f32_16x16x32_bf16 v[4:7], v[190:193], v[214:217], v[4:7]
	v_mfma_f32_16x16x32_bf16 v[12:15], v[182:185], v[222:225], v[12:15]
	v_mfma_f32_16x16x32_bf16 v[24:27], v[190:193], v[222:225], v[24:27]
	v_mfma_f32_16x16x32_bf16 v[44:47], v[182:185], v[230:233], v[44:47]
	v_mfma_f32_16x16x32_bf16 v[56:59], v[190:193], v[230:233], v[56:59]
	v_mfma_f32_16x16x32_bf16 v[68:71], v[182:185], v[238:241], v[68:71]
	v_mfma_f32_16x16x32_bf16 v[80:83], v[190:193], v[238:241], v[80:83]
	v_mfma_f32_16x16x32_bf16 v[0:3], v[186:189], v[218:221], v[0:3]
	v_mfma_f32_16x16x32_bf16 v[4:7], v[194:197], v[218:221], v[4:7]
	v_mfma_f32_16x16x32_bf16 v[12:15], v[186:189], v[226:229], v[12:15]
	v_mfma_f32_16x16x32_bf16 v[24:27], v[194:197], v[226:229], v[24:27]
	v_mfma_f32_16x16x32_bf16 v[44:47], v[186:189], v[234:237], v[44:47]
	v_mfma_f32_16x16x32_bf16 v[56:59], v[194:197], v[234:237], v[56:59]
	v_mfma_f32_16x16x32_bf16 v[68:71], v[186:189], v[242:245], v[68:71]
	v_mfma_f32_16x16x32_bf16 v[80:83], v[194:197], v[242:245], v[80:83]
	s_setprio 0
	s_setprio 1
	v_mfma_f32_16x16x32_bf16 v[20:23], v[198:201], v[214:217], v[20:23]
	v_mfma_f32_16x16x32_bf16 v[36:39], v[206:209], v[214:217], v[36:39]
	v_mfma_f32_16x16x32_bf16 v[48:51], v[198:201], v[222:225], v[48:51]
	v_mfma_f32_16x16x32_bf16 v[60:63], v[206:209], v[222:225], v[60:63]
	v_mfma_f32_16x16x32_bf16 v[72:75], v[198:201], v[230:233], v[72:75]
	v_mfma_f32_16x16x32_bf16 v[88:91], v[206:209], v[230:233], v[88:91]
	v_mfma_f32_16x16x32_bf16 v[96:99], v[198:201], v[238:241], v[96:99]
	v_mfma_f32_16x16x32_bf16 v[104:107], v[206:209], v[238:241], v[104:107]
	v_mfma_f32_16x16x32_bf16 v[20:23], v[202:205], v[218:221], v[20:23]
	v_mfma_f32_16x16x32_bf16 v[36:39], v[210:213], v[218:221], v[36:39]
	v_mfma_f32_16x16x32_bf16 v[48:51], v[202:205], v[226:229], v[48:51]
	v_mfma_f32_16x16x32_bf16 v[60:63], v[210:213], v[226:229], v[60:63]
	v_mfma_f32_16x16x32_bf16 v[72:75], v[202:205], v[234:237], v[72:75]
	v_mfma_f32_16x16x32_bf16 v[88:91], v[210:213], v[234:237], v[88:91]
	v_mfma_f32_16x16x32_bf16 v[96:99], v[202:205], v[242:245], v[96:99]
	v_mfma_f32_16x16x32_bf16 v[104:107], v[210:213], v[242:245], v[104:107]
	s_setprio 0
	s_barrier
	ds_read_b128 v[214:217], v180 offset:49152
	ds_read_b128 v[218:221], v180 offset:50176
	ds_read_b128 v[222:225], v180 offset:51200
	ds_read_b128 v[226:229], v180 offset:52224
	ds_read_b128 v[230:233], v180 offset:53248
	ds_read_b128 v[234:237], v180 offset:54272
	ds_read_b128 v[238:241], v180 offset:55296
	ds_read_b128 v[242:245], v180 offset:56320
	s_add_u32 s28, s64, 0x8000
	s_addc_u32 s29, s65, 0
	s_mov_b32 m0, s70
	s_nop 0
	global_load_lds_dwordx4 v176, s[28:29]
	s_nop 0
	s_mov_b32 m0, s71
	s_nop 0
	global_load_lds_dwordx4 v177, s[28:29]
	s_add_u32 s28, s64, 0xc000
	s_addc_u32 s29, s65, 0
	s_mov_b32 m0, s45
	s_nop 0
	global_load_lds_dwordx4 v176, s[28:29]
	s_nop 0
	s_mov_b32 m0, s46
	s_nop 0
	global_load_lds_dwordx4 v177, s[28:29]
	s_nop 0
	s_mov_b32 m0, s72
	s_nop 0
	global_load_lds_dwordx4 v176, s[62:63]
	s_nop 0
	s_mov_b32 m0, s44
	s_nop 0
	global_load_lds_dwordx4 v177, s[62:63]
	s_waitcnt vmcnt(8)
	s_waitcnt lgkmcnt(0)
	s_setprio 1
	s_barrier
	v_mfma_f32_16x16x32_bf16 v[28:31], v[182:185], v[214:217], v[28:31]
	v_mfma_f32_16x16x32_bf16 v[8:11], v[190:193], v[214:217], v[8:11]
	v_mfma_f32_16x16x32_bf16 v[40:43], v[182:185], v[222:225], v[40:43]
	v_mfma_f32_16x16x32_bf16 v[52:55], v[190:193], v[222:225], v[52:55]
	v_mfma_f32_16x16x32_bf16 v[84:87], v[182:185], v[230:233], v[84:87]
	v_mfma_f32_16x16x32_bf16 v[92:95], v[190:193], v[230:233], v[92:95]
	v_mfma_f32_16x16x32_bf16 v[112:115], v[182:185], v[238:241], v[112:115]
	v_mfma_f32_16x16x32_bf16 v[116:119], v[190:193], v[238:241], v[116:119]
	v_mfma_f32_16x16x32_bf16 v[28:31], v[186:189], v[218:221], v[28:31]
	v_mfma_f32_16x16x32_bf16 v[8:11], v[194:197], v[218:221], v[8:11]
	v_mfma_f32_16x16x32_bf16 v[40:43], v[186:189], v[226:229], v[40:43]
	v_mfma_f32_16x16x32_bf16 v[52:55], v[194:197], v[226:229], v[52:55]
	v_mfma_f32_16x16x32_bf16 v[84:87], v[186:189], v[234:237], v[84:87]
	v_mfma_f32_16x16x32_bf16 v[92:95], v[194:197], v[234:237], v[92:95]
	v_mfma_f32_16x16x32_bf16 v[112:115], v[186:189], v[242:245], v[112:115]
	v_mfma_f32_16x16x32_bf16 v[116:119], v[194:197], v[242:245], v[116:119]
	s_setprio 0
	s_setprio 1
	v_mfma_f32_16x16x32_bf16 v[16:19], v[198:201], v[214:217], v[16:19]
	v_mfma_f32_16x16x32_bf16 v[32:35], v[206:209], v[214:217], v[32:35]
	v_mfma_f32_16x16x32_bf16 v[64:67], v[198:201], v[222:225], v[64:67]
	v_mfma_f32_16x16x32_bf16 v[76:79], v[206:209], v[222:225], v[76:79]
	v_mfma_f32_16x16x32_bf16 v[100:103], v[198:201], v[230:233], v[100:103]
	v_mfma_f32_16x16x32_bf16 v[108:111], v[206:209], v[230:233], v[108:111]
	v_mfma_f32_16x16x32_bf16 v[120:123], v[198:201], v[238:241], v[120:123]
	v_mfma_f32_16x16x32_bf16 v[124:127], v[206:209], v[238:241], v[124:127]
	v_mfma_f32_16x16x32_bf16 v[16:19], v[202:205], v[218:221], v[16:19]
	v_mfma_f32_16x16x32_bf16 v[32:35], v[210:213], v[218:221], v[32:35]
	v_mfma_f32_16x16x32_bf16 v[64:67], v[202:205], v[226:229], v[64:67]
	v_mfma_f32_16x16x32_bf16 v[76:79], v[210:213], v[226:229], v[76:79]
	v_mfma_f32_16x16x32_bf16 v[100:103], v[202:205], v[234:237], v[100:103]
	v_mfma_f32_16x16x32_bf16 v[108:111], v[210:213], v[234:237], v[108:111]
	v_mfma_f32_16x16x32_bf16 v[120:123], v[202:205], v[242:245], v[120:123]
	v_mfma_f32_16x16x32_bf16 v[124:127], v[210:213], v[242:245], v[124:127]
	s_setprio 0
	s_barrier
	s_add_i32 s18, s18, 2
	s_add_u32 s55, s55, 0x10000
	s_addc_u32 s61, s61, 0
	s_add_u32 vcc_lo, vcc_lo, 0x10000
	s_addc_u32 vcc_hi, vcc_hi, 0
	s_cmpk_gt_u32 s18, 0xfd
	s_cbranch_scc0 .LBB0_618
	s_and_b64 vcc, exec, s[48:49]
	s_cbranch_vccz .LBB0_621
	s_barrier
	s_andn2_b64 vcc, exec, s[36:37]
	s_cbranch_vccnz .LBB0_623
	s_branch .LBB0_622
